# cache-policy hint: in-proj (PROJ) and gate/up (H) GEMM epilogue stores marked nt so the outputs do not displace the A/B slices in L2
# baseline (speedup 1.0000x reference)
; __device__ __forceinline__ unsigned cvt_pk_bf16(float lo, float hi) { f32x2c_t v = {lo, hi}; bf16x2c_t b = __builtin_convertvector(v, bf16x2c_t); return __builtin_bit_cast(unsigned, b); }
;     __device__ __forceinline__ void operator()(const f32x4 (&acc)[2][2][4][2], const Unit& u, int wr, int wc, int fr, int fq) const {
;         const float sc0 = (u.pn >= 3 && u.pn < 6) ? 0.08838834764831845f : ((u.pn >= 12 && u.pn < 15) ? 0.125f * 1.4426950408889634f : 1.f);
;         const int row0 = u.pm * BM + wr * 64 + fr, col0 = u.pn * BM + wc * 32 + 8 * fq;
; #pragma unroll
;         for (int ai = 0; ai < 2; ++ai)
; #pragma unroll
;             for (int m = 0; m < 4; ++m) { bf16_t* rowp = O + (size_t)(row0 + ai * HALF + m * 16) * ldc + col0; const float sc = sc0 * rs[row0 + ai * HALF + m * 16];
; #pragma unroll
;                 for (int bj = 0; bj < 2; ++bj) { const f32x4 v0 = acc[ai][bj][m][0] * sc, v1 = acc[ai][bj][m][1] * sc;
;                     u32x4 w; w.x = cvt_pk_bf16(v0[0], v0[1]); w.y = cvt_pk_bf16(v0[2], v0[3]); w.z = cvt_pk_bf16(v1[0], v1[1]); w.w = cvt_pk_bf16(v1[2], v1[3]);
;                     *(u32x4*)(rowp + bj * HALF) = w; } }
.LBB0_141:
	v_lshl_add_u32 v140, s83, 8, v148
	v_ashrrev_i32_e32 v141, 31, v140
	v_lshl_add_u64 v[144:145], v[140:141], 2, s[40:41]
	global_load_dword v164, v[144:145], off
	global_load_dword v166, v[144:145], off offset:64
	global_load_dword v168, v[144:145], off offset:128
	global_load_dword v170, v[144:145], off offset:192
	global_load_dword v172, v[144:145], off offset:512
	global_load_dword v174, v[144:145], off offset:576
	global_load_dword v176, v[144:145], off offset:640
	global_load_dword v178, v[144:145], off offset:704
	s_add_i32 s34, s82, -3
	s_add_i32 s22, s82, -12
	s_cmp_lt_u32 s22, 3
	s_cselect_b64 vcc, -1, 0
	s_cmp_gt_u32 s34, 2
	v_cndmask_b32_e32 v156, 1.0, v225, vcc
	s_cselect_b64 vcc, -1, 0
	v_lshl_or_b32 v146, s82, 8, v150
	v_cndmask_b32_e32 v162, v230, v156, vcc
	v_mov_b64_e32 v[142:143], s[36:37]
	v_ashrrev_i32_e32 v147, 31, v146
	v_mad_i64_i32 v[152:153], s[22:23], v140, s61, v[142:143]
	v_or_b32_e32 v154, 16, v140
	v_lshlrev_b64 v[146:147], 1, v[146:147]
	v_ashrrev_i32_e32 v155, 31, v154
	v_lshl_add_u64 v[152:153], v[152:153], 0, v[146:147]
	v_lshl_add_u64 v[156:157], v[154:155], 2, s[40:41]
	s_andn2_b64 vcc, exec, s[38:39]
	s_mov_b64 s[34:35], -1
	s_waitcnt vmcnt(0)
	v_mov_b32_e32 v141, v164
	v_mul_f32_e32 v158, v162, v141
	v_pk_mul_f32 v[128:129], v[128:129], v[158:159] op_sel_hi:[1,0]
	v_pk_mul_f32 v[126:127], v[126:127], v[158:159] op_sel_hi:[1,0]
	v_pk_mul_f32 v[124:125], v[124:125], v[158:159] op_sel_hi:[1,0]
	v_pk_mul_f32 v[122:123], v[122:123], v[158:159] op_sel_hi:[1,0]
	v_pk_mul_f32 v[120:121], v[120:121], v[158:159] op_sel_hi:[1,0]
	v_pk_mul_f32 v[118:119], v[118:119], v[158:159] op_sel_hi:[1,0]
	v_pk_mul_f32 v[160:161], v[116:117], v[158:159] op_sel_hi:[1,0]
	v_pk_mul_f32 v[158:159], v[114:115], v[158:159] op_sel_hi:[1,0]
	v_cvt_pk_bf16_f32 v114, v126, v127
	v_cvt_pk_bf16_f32 v115, v128, v129
	v_cvt_pk_bf16_f32 v116, v122, v123
	v_cvt_pk_bf16_f32 v117, v124, v125
	v_cvt_pk_bf16_f32 v118, v118, v119
	v_cvt_pk_bf16_f32 v119, v120, v121
	v_cvt_pk_bf16_f32 v120, v158, v159
	v_cvt_pk_bf16_f32 v121, v160, v161
	global_store_dwordx4 v[152:153], v[114:117], off nt
	global_store_dwordx4 v[152:153], v[118:121], off offset:256 nt
	v_or_b32_e32 v180, 32, v140
	v_mad_i64_i32 v[182:183], s[22:23], v154, s61, v[142:143]
	v_ashrrev_i32_e32 v181, 31, v180
	v_lshl_add_u64 v[182:183], v[182:183], 0, v[146:147]
	v_lshl_add_u64 v[184:185], v[180:181], 2, s[40:41]
	v_mov_b32_e32 v186, v166
	v_mul_f32_e32 v186, v162, v186
	v_pk_mul_f32 v[112:113], v[112:113], v[186:187] op_sel_hi:[1,0]
	v_pk_mul_f32 v[110:111], v[110:111], v[186:187] op_sel_hi:[1,0]
	v_pk_mul_f32 v[108:109], v[108:109], v[186:187] op_sel_hi:[1,0]
	v_pk_mul_f32 v[106:107], v[106:107], v[186:187] op_sel_hi:[1,0]
	v_pk_mul_f32 v[104:105], v[104:105], v[186:187] op_sel_hi:[1,0]
	v_pk_mul_f32 v[102:103], v[102:103], v[186:187] op_sel_hi:[1,0]
	v_pk_mul_f32 v[122:123], v[100:101], v[186:187] op_sel_hi:[1,0]
	v_pk_mul_f32 v[186:187], v[98:99], v[186:187] op_sel_hi:[1,0]
	v_cvt_pk_bf16_f32 v98, v110, v111
	v_cvt_pk_bf16_f32 v99, v112, v113
	v_cvt_pk_bf16_f32 v100, v106, v107
	v_cvt_pk_bf16_f32 v101, v108, v109
	v_cvt_pk_bf16_f32 v102, v102, v103
	v_cvt_pk_bf16_f32 v103, v104, v105
	v_cvt_pk_bf16_f32 v104, v186, v187
	v_cvt_pk_bf16_f32 v105, v122, v123
	global_store_dwordx4 v[182:183], v[98:101], off nt
	global_store_dwordx4 v[182:183], v[102:105], off offset:256 nt
	v_or_b32_e32 v122, 48, v140
	v_mad_i64_i32 v[124:125], s[22:23], v180, s61, v[142:143]
	v_ashrrev_i32_e32 v123, 31, v122
	v_lshl_add_u64 v[124:125], v[124:125], 0, v[146:147]
	v_lshl_add_u64 v[126:127], v[122:123], 2, s[40:41]
	v_mov_b32_e32 v128, v168
	v_mul_f32_e32 v128, v162, v128
	v_pk_mul_f32 v[96:97], v[96:97], v[128:129] op_sel_hi:[1,0]
	v_pk_mul_f32 v[94:95], v[94:95], v[128:129] op_sel_hi:[1,0]
	v_pk_mul_f32 v[92:93], v[92:93], v[128:129] op_sel_hi:[1,0]
	v_pk_mul_f32 v[90:91], v[90:91], v[128:129] op_sel_hi:[1,0]
	v_pk_mul_f32 v[84:85], v[84:85], v[128:129] op_sel_hi:[1,0]
	v_pk_mul_f32 v[82:83], v[82:83], v[128:129] op_sel_hi:[1,0]
	v_pk_mul_f32 v[106:107], v[76:77], v[128:129] op_sel_hi:[1,0]
	v_pk_mul_f32 v[128:129], v[74:75], v[128:129] op_sel_hi:[1,0]
	v_cvt_pk_bf16_f32 v74, v94, v95
	v_cvt_pk_bf16_f32 v75, v96, v97
	v_cvt_pk_bf16_f32 v76, v90, v91
	v_cvt_pk_bf16_f32 v77, v92, v93
	v_cvt_pk_bf16_f32 v82, v82, v83
	v_cvt_pk_bf16_f32 v83, v84, v85
	v_cvt_pk_bf16_f32 v84, v128, v129
	v_cvt_pk_bf16_f32 v85, v106, v107
	global_store_dwordx4 v[124:125], v[74:77], off nt
	global_store_dwordx4 v[124:125], v[82:85], off offset:256 nt
	v_mad_i64_i32 v[188:189], s[22:23], v122, s61, v[142:143]
	v_lshl_add_u64 v[188:189], v[188:189], 0, v[146:147]
	v_mov_b32_e32 v190, v170
	v_mul_f32_e32 v190, v162, v190
	v_pk_mul_f32 v[196:197], v[88:89], v[190:191] op_sel_hi:[1,0]
	v_pk_mul_f32 v[198:199], v[86:87], v[190:191] op_sel_hi:[1,0]
	v_pk_mul_f32 v[80:81], v[80:81], v[190:191] op_sel_hi:[1,0]
; __device__ __forceinline__ unsigned cvt_pk_bf16(float lo, float hi) { f32x2c_t v = {lo, hi}; bf16x2c_t b = __builtin_convertvector(v, bf16x2c_t); return __builtin_bit_cast(unsigned, b); }
;     __device__ __forceinline__ void operator()(const f32x4 (&acc)[2][2][4][2], const Unit& u, int wr, int wc, int fr, int fq) const {
;         const float sc0 = (u.pn >= 3 && u.pn < 6) ? 0.08838834764831845f : ((u.pn >= 12 && u.pn < 15) ? 0.125f * 1.4426950408889634f : 1.f);
;         const int row0 = u.pm * BM + wr * 64 + fr, col0 = u.pn * BM + wc * 32 + 8 * fq;
; #pragma unroll
;         for (int ai = 0; ai < 2; ++ai)
; #pragma unroll
;             for (int m = 0; m < 4; ++m) { bf16_t* rowp = O + (size_t)(row0 + ai * HALF + m * 16) * ldc + col0; const float sc = sc0 * rs[row0 + ai * HALF + m * 16];
; #pragma unroll
;                 for (int bj = 0; bj < 2; ++bj) { const f32x4 v0 = acc[ai][bj][m][0] * sc, v1 = acc[ai][bj][m][1] * sc;
;                     u32x4 w; w.x = cvt_pk_bf16(v0[0], v0[1]); w.y = cvt_pk_bf16(v0[2], v0[3]); w.z = cvt_pk_bf16(v1[0], v1[1]); w.w = cvt_pk_bf16(v1[2], v1[3]);
;                     *(u32x4*)(rowp + bj * HALF) = w; } }
	v_pk_mul_f32 v[78:79], v[78:79], v[190:191] op_sel_hi:[1,0]
	v_pk_mul_f32 v[72:73], v[72:73], v[190:191] op_sel_hi:[1,0]
	v_pk_mul_f32 v[70:71], v[70:71], v[190:191] op_sel_hi:[1,0]
	v_pk_mul_f32 v[86:87], v[68:69], v[190:191] op_sel_hi:[1,0]
	v_pk_mul_f32 v[190:191], v[66:67], v[190:191] op_sel_hi:[1,0]
	v_cvt_pk_bf16_f32 v66, v198, v199
	v_cvt_pk_bf16_f32 v67, v196, v197
	v_cvt_pk_bf16_f32 v68, v78, v79
	v_cvt_pk_bf16_f32 v69, v80, v81
	v_cvt_pk_bf16_f32 v70, v70, v71
	v_cvt_pk_bf16_f32 v71, v72, v73
	v_cvt_pk_bf16_f32 v72, v190, v191
	v_cvt_pk_bf16_f32 v73, v86, v87
	global_store_dwordx4 v[188:189], v[66:69], off nt
	global_store_dwordx4 v[188:189], v[70:73], off offset:256 nt
	v_add_u32_e32 v86, 0x80, v140
	v_mad_i64_i32 v[86:87], s[22:23], v86, s61, v[142:143]
	v_lshl_add_u64 v[86:87], v[86:87], 0, v[146:147]
	v_mov_b32_e32 v88, v172
	v_mul_f32_e32 v88, v162, v88
	v_pk_mul_f32 v[64:65], v[64:65], v[88:89] op_sel_hi:[1,0]
	v_pk_mul_f32 v[62:63], v[62:63], v[88:89] op_sel_hi:[1,0]
	v_pk_mul_f32 v[60:61], v[60:61], v[88:89] op_sel_hi:[1,0]
	v_pk_mul_f32 v[58:59], v[58:59], v[88:89] op_sel_hi:[1,0]
	v_pk_mul_f32 v[56:57], v[56:57], v[88:89] op_sel_hi:[1,0]
	v_pk_mul_f32 v[54:55], v[54:55], v[88:89] op_sel_hi:[1,0]
	v_pk_mul_f32 v[90:91], v[48:49], v[88:89] op_sel_hi:[1,0]
	v_pk_mul_f32 v[88:89], v[46:47], v[88:89] op_sel_hi:[1,0]
	v_cvt_pk_bf16_f32 v46, v62, v63
	v_cvt_pk_bf16_f32 v47, v64, v65
	v_cvt_pk_bf16_f32 v48, v58, v59
	v_cvt_pk_bf16_f32 v49, v60, v61
	v_cvt_pk_bf16_f32 v54, v54, v55
	v_cvt_pk_bf16_f32 v55, v56, v57
	v_cvt_pk_bf16_f32 v56, v88, v89
	v_cvt_pk_bf16_f32 v57, v90, v91
	global_store_dwordx4 v[86:87], v[46:49], off nt
	global_store_dwordx4 v[86:87], v[54:57], off offset:256 nt
	v_add_u32_e32 v152, 0x90, v140
	v_mad_i64_i32 v[152:153], s[22:23], v152, s61, v[142:143]
	v_lshl_add_u64 v[152:153], v[152:153], 0, v[146:147]
	v_mov_b32_e32 v154, v174
	v_mul_f32_e32 v154, v162, v154
	v_pk_mul_f32 v[52:53], v[52:53], v[154:155] op_sel_hi:[1,0]
	v_pk_mul_f32 v[50:51], v[50:51], v[154:155] op_sel_hi:[1,0]
	v_pk_mul_f32 v[44:45], v[44:45], v[154:155] op_sel_hi:[1,0]
	v_pk_mul_f32 v[42:43], v[42:43], v[154:155] op_sel_hi:[1,0]
	v_pk_mul_f32 v[40:41], v[40:41], v[154:155] op_sel_hi:[1,0]
	v_pk_mul_f32 v[38:39], v[38:39], v[154:155] op_sel_hi:[1,0]
	v_pk_mul_f32 v[160:161], v[32:33], v[154:155] op_sel_hi:[1,0]
	v_pk_mul_f32 v[154:155], v[30:31], v[154:155] op_sel_hi:[1,0]
	v_cvt_pk_bf16_f32 v30, v50, v51
	v_cvt_pk_bf16_f32 v31, v52, v53
	v_cvt_pk_bf16_f32 v32, v42, v43
	v_cvt_pk_bf16_f32 v33, v44, v45
	v_cvt_pk_bf16_f32 v38, v38, v39
	v_cvt_pk_bf16_f32 v39, v40, v41
	v_cvt_pk_bf16_f32 v40, v154, v155
	v_cvt_pk_bf16_f32 v41, v160, v161
	global_store_dwordx4 v[152:153], v[30:33], off nt
	global_store_dwordx4 v[152:153], v[38:41], off offset:256 nt
	v_add_u32_e32 v42, 0xa0, v140
	v_mad_i64_i32 v[42:43], s[22:23], v42, s61, v[142:143]
	v_lshl_add_u64 v[42:43], v[42:43], 0, v[146:147]
	v_mov_b32_e32 v44, v176
	v_mul_f32_e32 v44, v162, v44
	v_pk_mul_f32 v[36:37], v[36:37], v[44:45] op_sel_hi:[1,0]
	v_pk_mul_f32 v[34:35], v[34:35], v[44:45] op_sel_hi:[1,0]
	v_pk_mul_f32 v[28:29], v[28:29], v[44:45] op_sel_hi:[1,0]
	v_pk_mul_f32 v[26:27], v[26:27], v[44:45] op_sel_hi:[1,0]
	v_pk_mul_f32 v[24:25], v[24:25], v[44:45] op_sel_hi:[1,0]
	v_pk_mul_f32 v[22:23], v[22:23], v[44:45] op_sel_hi:[1,0]
	v_pk_mul_f32 v[50:51], v[20:21], v[44:45] op_sel_hi:[1,0]
	v_pk_mul_f32 v[44:45], v[18:19], v[44:45] op_sel_hi:[1,0]
	v_cvt_pk_bf16_f32 v18, v34, v35
	v_cvt_pk_bf16_f32 v19, v36, v37
	v_cvt_pk_bf16_f32 v20, v26, v27
	v_cvt_pk_bf16_f32 v21, v28, v29
	v_cvt_pk_bf16_f32 v22, v22, v23
	v_cvt_pk_bf16_f32 v23, v24, v25
	v_cvt_pk_bf16_f32 v24, v44, v45
	v_cvt_pk_bf16_f32 v25, v50, v51
	global_store_dwordx4 v[42:43], v[18:21], off nt
	global_store_dwordx4 v[42:43], v[22:25], off offset:256 nt
	v_add_u32_e32 v58, 0xb0, v140
	v_mad_i64_i32 v[58:59], s[22:23], v58, s61, v[142:143]
	v_lshl_add_u64 v[58:59], v[58:59], 0, v[146:147]
	v_mov_b32_e32 v60, v178
	v_mul_f32_e32 v60, v162, v60
	v_pk_mul_f32 v[16:17], v[16:17], v[60:61] op_sel_hi:[1,0]
	v_pk_mul_f32 v[14:15], v[14:15], v[60:61] op_sel_hi:[1,0]
	v_pk_mul_f32 v[12:13], v[12:13], v[60:61] op_sel_hi:[1,0]
	v_pk_mul_f32 v[10:11], v[10:11], v[60:61] op_sel_hi:[1,0]
	v_pk_mul_f32 v[8:9], v[8:9], v[60:61] op_sel_hi:[1,0]
	v_pk_mul_f32 v[6:7], v[6:7], v[60:61] op_sel_hi:[1,0]
	v_pk_mul_f32 v[62:63], v[4:5], v[60:61] op_sel_hi:[1,0]
	v_pk_mul_f32 v[60:61], v[2:3], v[60:61] op_sel_hi:[1,0]
	v_cvt_pk_bf16_f32 v2, v14, v15
	v_cvt_pk_bf16_f32 v3, v16, v17
	v_cvt_pk_bf16_f32 v4, v10, v11
	v_cvt_pk_bf16_f32 v5, v12, v13
	v_cvt_pk_bf16_f32 v6, v6, v7
	v_cvt_pk_bf16_f32 v7, v8, v9
	v_cvt_pk_bf16_f32 v8, v60, v61
	v_cvt_pk_bf16_f32 v9, v62, v63
	global_store_dwordx4 v[58:59], v[2:5], off nt
	global_store_dwordx4 v[58:59], v[6:9], off offset:256 nt
	s_cbranch_vccnz .LBB0_134
	s_andn2_b64 vcc, exec, s[26:27]
	s_cbranch_vccnz .LBB0_133
	s_barrier
	s_branch .LBB0_133

; __device__ __forceinline__ unsigned cvt_pk_bf16(float lo, float hi) { f32x2c_t v = {lo, hi}; bf16x2c_t b = __builtin_convertvector(v, bf16x2c_t); return __builtin_bit_cast(unsigned, b); }
;     __device__ __forceinline__ static float sw(float g, float u) { return g * __builtin_amdgcn_rcpf(1.f + __builtin_amdgcn_exp2f(-1.4426950408889634f * g)) * u; }
;     __device__ __forceinline__ void operator()(const f32x4 (&acc)[2][2][4][2], const Unit& u, int wr, int wc, int fr, int fq) const {
;         const int row0 = u.pm * BM + wr * 64 + fr, col0 = u.pn * HALF + wc * 32 + 8 * fq;
; #pragma unroll
;         for (int ai = 0; ai < 2; ++ai)
; #pragma unroll
;             for (int m = 0; m < 4; ++m) { bf16_t* rowp = O + (size_t)(row0 + ai * HALF + m * 16) * ldc + col0;
;                 const float r_ = rs[row0 + ai * HALF + m * 16];
;                 const f32x4 g0 = acc[ai][0][m][0] * r_, g1 = acc[ai][0][m][1] * r_, u0 = acc[ai][1][m][0] * r_, u1 = acc[ai][1][m][1] * r_;
;                 u32x4 w; w.x = cvt_pk_bf16(sw(g0[0], u0[0]), sw(g0[1], u0[1])); w.y = cvt_pk_bf16(sw(g0[2], u0[2]), sw(g0[3], u0[3]));
;                 w.z = cvt_pk_bf16(sw(g1[0], u1[0]), sw(g1[1], u1[1])); w.w = cvt_pk_bf16(sw(g1[2], u1[2]), sw(g1[3], u1[3]));
;                 *(u32x4*)rowp = w; }
.LBB0_707:
	v_lshl_or_b32 v144, s82, 7, v150
	v_lshl_add_u32 v140, s83, 8, v148
	v_ashrrev_i32_e32 v145, 31, v144
	v_mov_b64_e32 v[142:143], s[36:37]
	v_ashrrev_i32_e32 v141, 31, v140
	v_mad_i64_i32 v[146:147], s[22:23], v140, s73, v[142:143]
	v_lshlrev_b64 v[144:145], 1, v[144:145]
	v_lshl_add_u64 v[152:153], v[146:147], 0, v[144:145]
	v_lshl_add_u64 v[146:147], v[140:141], 2, s[42:43]
	global_load_dword v164, v[146:147], off
	global_load_dword v166, v[146:147], off offset:64
	global_load_dword v168, v[146:147], off offset:128
	global_load_dword v170, v[146:147], off offset:192
	global_load_dword v172, v[146:147], off offset:512
	global_load_dword v174, v[146:147], off offset:576
	global_load_dword v176, v[146:147], off offset:640
	global_load_dword v178, v[146:147], off offset:704
	s_mov_b64 s[34:35], -1
	s_andn2_b64 vcc, exec, s[40:41]
	v_readlane_b32 s91, v255, 54
	s_waitcnt vmcnt(0)
	v_mov_b32_e32 v154, v164
	v_pk_mul_f32 v[126:127], v[126:127], v[154:155] op_sel_hi:[1,0]
	v_pk_mul_f32 v[156:157], v[116:117], v[154:155] op_sel_hi:[1,0]
	v_pk_mul_f32 v[116:117], v[114:115], v[154:155] op_sel_hi:[1,0]
	v_mul_f32_e32 v114, 0xbfb8aa3b, v126
	v_mul_f32_e32 v115, 0xbfb8aa3b, v127
	v_exp_f32_e32 v114, v114
	v_exp_f32_e32 v115, v115
	v_pk_mul_f32 v[118:119], v[118:119], v[154:155] op_sel_hi:[1,0]
	v_pk_mul_f32 v[128:129], v[128:129], v[154:155] op_sel_hi:[1,0]
	v_add_f32_e32 v114, 1.0, v114
	v_add_f32_e32 v115, 1.0, v115
	v_rcp_f32_e32 v114, v114
	v_rcp_f32_e32 v115, v115
	v_pk_mul_f32 v[120:121], v[120:121], v[154:155] op_sel_hi:[1,0]
	v_pk_mul_f32 v[122:123], v[122:123], v[154:155] op_sel_hi:[1,0]
	v_pk_mul_f32 v[124:125], v[124:125], v[154:155] op_sel_hi:[1,0]
	v_pk_mul_f32 v[114:115], v[126:127], v[114:115]
	s_nop 0
	v_pk_mul_f32 v[114:115], v[118:119], v[114:115]
	s_nop 0
	v_cvt_pk_bf16_f32 v114, v114, v115
	v_mul_f32_e32 v115, 0xbfb8aa3b, v128
	v_exp_f32_e32 v115, v115
	s_nop 0
	v_add_f32_e32 v115, 1.0, v115
	v_rcp_f32_e32 v118, v115
	v_mul_f32_e32 v115, 0xbfb8aa3b, v129
	v_exp_f32_e32 v115, v115
	s_nop 0
	v_add_f32_e32 v115, 1.0, v115
	v_rcp_f32_e32 v119, v115
	s_nop 0
	v_pk_mul_f32 v[118:119], v[128:129], v[118:119]
	s_nop 0
	v_pk_mul_f32 v[118:119], v[120:121], v[118:119]
	s_nop 0
	v_cvt_pk_bf16_f32 v115, v118, v119
	v_mul_f32_e32 v118, 0xbfb8aa3b, v122
	v_mul_f32_e32 v119, 0xbfb8aa3b, v123
	v_exp_f32_e32 v118, v118
	v_exp_f32_e32 v119, v119
	v_add_f32_e32 v118, 1.0, v118
	v_add_f32_e32 v119, 1.0, v119
	v_rcp_f32_e32 v118, v118
	v_rcp_f32_e32 v119, v119
	s_nop 0
	v_pk_mul_f32 v[118:119], v[122:123], v[118:119]
	s_nop 0
	v_pk_mul_f32 v[116:117], v[116:117], v[118:119]
	s_nop 0
	v_cvt_pk_bf16_f32 v116, v116, v117
	v_mul_f32_e32 v117, 0xbfb8aa3b, v124
	v_exp_f32_e32 v117, v117
	s_nop 0
	v_add_f32_e32 v117, 1.0, v117
	v_rcp_f32_e32 v118, v117
	v_mul_f32_e32 v117, 0xbfb8aa3b, v125
	v_exp_f32_e32 v117, v117
	s_nop 0
	v_add_f32_e32 v117, 1.0, v117
	v_rcp_f32_e32 v119, v117
	s_nop 0
	v_pk_mul_f32 v[118:119], v[124:125], v[118:119]
	s_nop 0
	v_pk_mul_f32 v[118:119], v[156:157], v[118:119]
	s_nop 0
	v_cvt_pk_bf16_f32 v117, v118, v119
	global_store_dwordx4 v[152:153], v[114:117], off nt
	s_nop 1
	v_or_b32_e32 v122, 16, v140
	v_ashrrev_i32_e32 v123, 31, v122
	v_mad_i64_i32 v[120:121], s[22:23], v122, s73, v[142:143]
	v_lshl_add_u64 v[122:123], v[122:123], 2, s[42:43]
	v_lshl_add_u64 v[120:121], v[120:121], 0, v[144:145]
	v_mov_b32_e32 v122, v166
	v_pk_mul_f32 v[110:111], v[110:111], v[122:123] op_sel_hi:[1,0]
	v_pk_mul_f32 v[118:119], v[100:101], v[122:123] op_sel_hi:[1,0]
	v_pk_mul_f32 v[100:101], v[98:99], v[122:123] op_sel_hi:[1,0]
	v_mul_f32_e32 v98, 0xbfb8aa3b, v110
	v_mul_f32_e32 v99, 0xbfb8aa3b, v111
	v_exp_f32_e32 v98, v98
	v_exp_f32_e32 v99, v99
	v_pk_mul_f32 v[102:103], v[102:103], v[122:123] op_sel_hi:[1,0]
	v_pk_mul_f32 v[112:113], v[112:113], v[122:123] op_sel_hi:[1,0]
	v_add_f32_e32 v98, 1.0, v98
	v_add_f32_e32 v99, 1.0, v99
	v_rcp_f32_e32 v98, v98
	v_rcp_f32_e32 v99, v99
	v_pk_mul_f32 v[104:105], v[104:105], v[122:123] op_sel_hi:[1,0]
	v_pk_mul_f32 v[106:107], v[106:107], v[122:123] op_sel_hi:[1,0]
	v_pk_mul_f32 v[108:109], v[108:109], v[122:123] op_sel_hi:[1,0]
	v_pk_mul_f32 v[98:99], v[110:111], v[98:99]
	s_nop 0
	v_pk_mul_f32 v[98:99], v[102:103], v[98:99]
	s_nop 0
	v_cvt_pk_bf16_f32 v98, v98, v99
	v_mul_f32_e32 v99, 0xbfb8aa3b, v112
	v_exp_f32_e32 v99, v99
	s_nop 0
	v_add_f32_e32 v99, 1.0, v99
	v_rcp_f32_e32 v102, v99
	v_mul_f32_e32 v99, 0xbfb8aa3b, v113
	v_exp_f32_e32 v99, v99
	s_nop 0
	v_add_f32_e32 v99, 1.0, v99
	v_rcp_f32_e32 v103, v99
	s_nop 0
	v_pk_mul_f32 v[102:103], v[112:113], v[102:103]
	s_nop 0
	v_pk_mul_f32 v[102:103], v[104:105], v[102:103]
	s_nop 0
	v_cvt_pk_bf16_f32 v99, v102, v103
	v_mul_f32_e32 v102, 0xbfb8aa3b, v106
	v_mul_f32_e32 v103, 0xbfb8aa3b, v107
	v_exp_f32_e32 v102, v102
	v_exp_f32_e32 v103, v103
	v_add_f32_e32 v102, 1.0, v102
	v_add_f32_e32 v103, 1.0, v103
	v_rcp_f32_e32 v102, v102
	v_rcp_f32_e32 v103, v103
	s_nop 0
	v_pk_mul_f32 v[102:103], v[106:107], v[102:103]
	s_nop 0
	v_pk_mul_f32 v[100:101], v[100:101], v[102:103]
	s_nop 0
	v_cvt_pk_bf16_f32 v100, v100, v101
	v_mul_f32_e32 v101, 0xbfb8aa3b, v108
	v_exp_f32_e32 v101, v101
	s_nop 0
	v_add_f32_e32 v101, 1.0, v101
	v_rcp_f32_e32 v102, v101
	v_mul_f32_e32 v101, 0xbfb8aa3b, v109
	v_exp_f32_e32 v101, v101
	s_nop 0
	v_add_f32_e32 v101, 1.0, v101
	v_rcp_f32_e32 v103, v101
	s_nop 0
	v_pk_mul_f32 v[102:103], v[108:109], v[102:103]
	s_nop 0
	v_pk_mul_f32 v[102:103], v[118:119], v[102:103]
	s_nop 0
	v_cvt_pk_bf16_f32 v101, v102, v103
	global_store_dwordx4 v[120:121], v[98:101], off nt
	s_nop 1
	v_or_b32_e32 v106, 32, v140
	v_ashrrev_i32_e32 v107, 31, v106
; __device__ __forceinline__ unsigned cvt_pk_bf16(float lo, float hi) { f32x2c_t v = {lo, hi}; bf16x2c_t b = __builtin_convertvector(v, bf16x2c_t); return __builtin_bit_cast(unsigned, b); }
;     __device__ __forceinline__ static float sw(float g, float u) { return g * __builtin_amdgcn_rcpf(1.f + __builtin_amdgcn_exp2f(-1.4426950408889634f * g)) * u; }
;     __device__ __forceinline__ void operator()(const f32x4 (&acc)[2][2][4][2], const Unit& u, int wr, int wc, int fr, int fq) const {
;         const int row0 = u.pm * BM + wr * 64 + fr, col0 = u.pn * HALF + wc * 32 + 8 * fq;
; #pragma unroll
;         for (int ai = 0; ai < 2; ++ai)
; #pragma unroll
;             for (int m = 0; m < 4; ++m) { bf16_t* rowp = O + (size_t)(row0 + ai * HALF + m * 16) * ldc + col0;
;                 const float r_ = rs[row0 + ai * HALF + m * 16];
;                 const f32x4 g0 = acc[ai][0][m][0] * r_, g1 = acc[ai][0][m][1] * r_, u0 = acc[ai][1][m][0] * r_, u1 = acc[ai][1][m][1] * r_;
;                 u32x4 w; w.x = cvt_pk_bf16(sw(g0[0], u0[0]), sw(g0[1], u0[1])); w.y = cvt_pk_bf16(sw(g0[2], u0[2]), sw(g0[3], u0[3]));
;                 w.z = cvt_pk_bf16(sw(g1[0], u1[0]), sw(g1[1], u1[1])); w.w = cvt_pk_bf16(sw(g1[2], u1[2]), sw(g1[3], u1[3]));
;                 *(u32x4*)rowp = w; }
	v_mad_i64_i32 v[104:105], s[22:23], v106, s73, v[142:143]
	v_lshl_add_u64 v[106:107], v[106:107], 2, s[42:43]
	v_lshl_add_u64 v[104:105], v[104:105], 0, v[144:145]
	v_mov_b32_e32 v106, v168
	v_pk_mul_f32 v[94:95], v[94:95], v[106:107] op_sel_hi:[1,0]
	v_pk_mul_f32 v[102:103], v[84:85], v[106:107] op_sel_hi:[1,0]
	v_pk_mul_f32 v[84:85], v[82:83], v[106:107] op_sel_hi:[1,0]
	v_mul_f32_e32 v82, 0xbfb8aa3b, v94
	v_mul_f32_e32 v83, 0xbfb8aa3b, v95
	v_exp_f32_e32 v82, v82
	v_exp_f32_e32 v83, v83
	v_pk_mul_f32 v[86:87], v[86:87], v[106:107] op_sel_hi:[1,0]
	v_pk_mul_f32 v[96:97], v[96:97], v[106:107] op_sel_hi:[1,0]
	v_add_f32_e32 v82, 1.0, v82
	v_add_f32_e32 v83, 1.0, v83
	v_rcp_f32_e32 v82, v82
	v_rcp_f32_e32 v83, v83
	v_pk_mul_f32 v[88:89], v[88:89], v[106:107] op_sel_hi:[1,0]
	v_pk_mul_f32 v[90:91], v[90:91], v[106:107] op_sel_hi:[1,0]
	v_pk_mul_f32 v[92:93], v[92:93], v[106:107] op_sel_hi:[1,0]
	v_pk_mul_f32 v[82:83], v[94:95], v[82:83]
	s_nop 0
	v_pk_mul_f32 v[82:83], v[86:87], v[82:83]
	s_nop 0
	v_cvt_pk_bf16_f32 v82, v82, v83
	v_mul_f32_e32 v83, 0xbfb8aa3b, v96
	v_exp_f32_e32 v83, v83
	s_nop 0
	v_add_f32_e32 v83, 1.0, v83
	v_rcp_f32_e32 v86, v83
	v_mul_f32_e32 v83, 0xbfb8aa3b, v97
	v_exp_f32_e32 v83, v83
	s_nop 0
	v_add_f32_e32 v83, 1.0, v83
	v_rcp_f32_e32 v87, v83
	s_nop 0
	v_pk_mul_f32 v[86:87], v[96:97], v[86:87]
	s_nop 0
	v_pk_mul_f32 v[86:87], v[88:89], v[86:87]
	s_nop 0
	v_cvt_pk_bf16_f32 v83, v86, v87
	v_mul_f32_e32 v86, 0xbfb8aa3b, v90
	v_mul_f32_e32 v87, 0xbfb8aa3b, v91
	v_exp_f32_e32 v86, v86
	v_exp_f32_e32 v87, v87
	v_add_f32_e32 v86, 1.0, v86
	v_add_f32_e32 v87, 1.0, v87
	v_rcp_f32_e32 v86, v86
	v_rcp_f32_e32 v87, v87
	s_nop 0
	v_pk_mul_f32 v[86:87], v[90:91], v[86:87]
	s_nop 0
	v_pk_mul_f32 v[84:85], v[84:85], v[86:87]
	s_nop 0
	v_cvt_pk_bf16_f32 v84, v84, v85
	v_mul_f32_e32 v85, 0xbfb8aa3b, v92
	v_exp_f32_e32 v85, v85
	s_nop 0
	v_add_f32_e32 v85, 1.0, v85
	v_rcp_f32_e32 v86, v85
	v_mul_f32_e32 v85, 0xbfb8aa3b, v93
	v_exp_f32_e32 v85, v85
	s_nop 0
	v_add_f32_e32 v85, 1.0, v85
	v_rcp_f32_e32 v87, v85
	s_nop 0
	v_pk_mul_f32 v[86:87], v[92:93], v[86:87]
	s_nop 0
	v_pk_mul_f32 v[86:87], v[102:103], v[86:87]
	s_nop 0
	v_cvt_pk_bf16_f32 v85, v86, v87
	global_store_dwordx4 v[104:105], v[82:85], off nt
	s_nop 1
	v_or_b32_e32 v90, 48, v140
	v_ashrrev_i32_e32 v91, 31, v90
	v_mad_i64_i32 v[88:89], s[22:23], v90, s73, v[142:143]
	v_lshl_add_u64 v[90:91], v[90:91], 2, s[42:43]
	v_lshl_add_u64 v[88:89], v[88:89], 0, v[144:145]
	v_mov_b32_e32 v90, v170
	v_pk_mul_f32 v[78:79], v[78:79], v[90:91] op_sel_hi:[1,0]
	v_pk_mul_f32 v[86:87], v[70:71], v[90:91] op_sel_hi:[1,0]
	v_pk_mul_f32 v[70:71], v[68:69], v[90:91] op_sel_hi:[1,0]
	v_pk_mul_f32 v[68:69], v[66:67], v[90:91] op_sel_hi:[1,0]
	v_mul_f32_e32 v66, 0xbfb8aa3b, v78
	v_mul_f32_e32 v67, 0xbfb8aa3b, v79
	v_exp_f32_e32 v66, v66
	v_exp_f32_e32 v67, v67
	v_pk_mul_f32 v[80:81], v[80:81], v[90:91] op_sel_hi:[1,0]
	v_pk_mul_f32 v[72:73], v[72:73], v[90:91] op_sel_hi:[1,0]
	v_add_f32_e32 v66, 1.0, v66
	v_add_f32_e32 v67, 1.0, v67
	v_rcp_f32_e32 v66, v66
	v_rcp_f32_e32 v67, v67
	v_pk_mul_f32 v[74:75], v[74:75], v[90:91] op_sel_hi:[1,0]
	v_pk_mul_f32 v[76:77], v[76:77], v[90:91] op_sel_hi:[1,0]
	v_pk_mul_f32 v[66:67], v[78:79], v[66:67]
	s_nop 0
	v_pk_mul_f32 v[66:67], v[86:87], v[66:67]
	s_nop 0
	v_cvt_pk_bf16_f32 v66, v66, v67
	v_mul_f32_e32 v67, 0xbfb8aa3b, v80
	v_exp_f32_e32 v67, v67
	s_nop 0
	v_add_f32_e32 v67, 1.0, v67
	v_rcp_f32_e32 v78, v67
	v_mul_f32_e32 v67, 0xbfb8aa3b, v81
	v_exp_f32_e32 v67, v67
	s_nop 0
	v_add_f32_e32 v67, 1.0, v67
	v_rcp_f32_e32 v79, v67
	s_nop 0
	v_pk_mul_f32 v[78:79], v[80:81], v[78:79]
	s_nop 0
	v_pk_mul_f32 v[72:73], v[72:73], v[78:79]
	s_nop 0
	v_cvt_pk_bf16_f32 v67, v72, v73
	v_mul_f32_e32 v72, 0xbfb8aa3b, v74
	v_mul_f32_e32 v73, 0xbfb8aa3b, v75
	v_exp_f32_e32 v72, v72
	v_exp_f32_e32 v73, v73
	v_add_f32_e32 v72, 1.0, v72
	v_add_f32_e32 v73, 1.0, v73
	v_rcp_f32_e32 v72, v72
	v_rcp_f32_e32 v73, v73
	s_nop 0
	v_pk_mul_f32 v[72:73], v[74:75], v[72:73]
	s_nop 0
	v_pk_mul_f32 v[68:69], v[68:69], v[72:73]
	s_nop 0
	v_cvt_pk_bf16_f32 v68, v68, v69
	v_mul_f32_e32 v69, 0xbfb8aa3b, v76
	v_exp_f32_e32 v69, v69
	s_nop 0
	v_add_f32_e32 v69, 1.0, v69
	v_rcp_f32_e32 v72, v69
	v_mul_f32_e32 v69, 0xbfb8aa3b, v77
	v_exp_f32_e32 v69, v69
	s_nop 0
	v_add_f32_e32 v69, 1.0, v69
	v_rcp_f32_e32 v73, v69
	s_nop 0
	v_pk_mul_f32 v[72:73], v[76:77], v[72:73]
	s_nop 0
	v_pk_mul_f32 v[70:71], v[70:71], v[72:73]
	s_nop 0
	v_cvt_pk_bf16_f32 v69, v70, v71
	global_store_dwordx4 v[88:89], v[66:69], off nt
	v_mov_b32_e32 v74, v172
	v_pk_mul_f32 v[62:63], v[62:63], v[74:75] op_sel_hi:[1,0]
	v_pk_mul_f32 v[70:71], v[54:55], v[74:75] op_sel_hi:[1,0]
	v_pk_mul_f32 v[54:55], v[52:53], v[74:75] op_sel_hi:[1,0]
	v_pk_mul_f32 v[52:53], v[50:51], v[74:75] op_sel_hi:[1,0]
	v_mul_f32_e32 v50, 0xbfb8aa3b, v62
	v_mul_f32_e32 v51, 0xbfb8aa3b, v63
	v_exp_f32_e32 v50, v50
	v_exp_f32_e32 v51, v51
	v_pk_mul_f32 v[64:65], v[64:65], v[74:75] op_sel_hi:[1,0]
	v_pk_mul_f32 v[56:57], v[56:57], v[74:75] op_sel_hi:[1,0]
	v_add_f32_e32 v50, 1.0, v50
	v_add_f32_e32 v51, 1.0, v51
	v_rcp_f32_e32 v50, v50
	v_rcp_f32_e32 v51, v51
	v_pk_mul_f32 v[58:59], v[58:59], v[74:75] op_sel_hi:[1,0]
	v_pk_mul_f32 v[60:61], v[60:61], v[74:75] op_sel_hi:[1,0]
	v_add_u32_e32 v72, 0x80, v140
	v_pk_mul_f32 v[50:51], v[62:63], v[50:51]
	v_mad_i64_i32 v[72:73], s[22:23], v72, s73, v[142:143]
	v_pk_mul_f32 v[50:51], v[70:71], v[50:51]
	v_lshl_add_u64 v[72:73], v[72:73], 0, v[144:145]
	v_cvt_pk_bf16_f32 v50, v50, v51
	v_mul_f32_e32 v51, 0xbfb8aa3b, v64
	v_exp_f32_e32 v51, v51
	s_nop 0
	v_add_f32_e32 v51, 1.0, v51
	v_rcp_f32_e32 v62, v51
; __device__ __forceinline__ unsigned cvt_pk_bf16(float lo, float hi) { f32x2c_t v = {lo, hi}; bf16x2c_t b = __builtin_convertvector(v, bf16x2c_t); return __builtin_bit_cast(unsigned, b); }
;     __device__ __forceinline__ static float sw(float g, float u) { return g * __builtin_amdgcn_rcpf(1.f + __builtin_amdgcn_exp2f(-1.4426950408889634f * g)) * u; }
;     __device__ __forceinline__ void operator()(const f32x4 (&acc)[2][2][4][2], const Unit& u, int wr, int wc, int fr, int fq) const {
;         const int row0 = u.pm * BM + wr * 64 + fr, col0 = u.pn * HALF + wc * 32 + 8 * fq;
; #pragma unroll
;         for (int ai = 0; ai < 2; ++ai)
; #pragma unroll
;             for (int m = 0; m < 4; ++m) { bf16_t* rowp = O + (size_t)(row0 + ai * HALF + m * 16) * ldc + col0;
;                 const float r_ = rs[row0 + ai * HALF + m * 16];
;                 const f32x4 g0 = acc[ai][0][m][0] * r_, g1 = acc[ai][0][m][1] * r_, u0 = acc[ai][1][m][0] * r_, u1 = acc[ai][1][m][1] * r_;
;                 u32x4 w; w.x = cvt_pk_bf16(sw(g0[0], u0[0]), sw(g0[1], u0[1])); w.y = cvt_pk_bf16(sw(g0[2], u0[2]), sw(g0[3], u0[3]));
;                 w.z = cvt_pk_bf16(sw(g1[0], u1[0]), sw(g1[1], u1[1])); w.w = cvt_pk_bf16(sw(g1[2], u1[2]), sw(g1[3], u1[3]));
;                 *(u32x4*)rowp = w; }
	v_mul_f32_e32 v51, 0xbfb8aa3b, v65
	v_exp_f32_e32 v51, v51
	s_nop 0
	v_add_f32_e32 v51, 1.0, v51
	v_rcp_f32_e32 v63, v51
	s_nop 0
	v_pk_mul_f32 v[62:63], v[64:65], v[62:63]
	s_nop 0
	v_pk_mul_f32 v[56:57], v[56:57], v[62:63]
	s_nop 0
	v_cvt_pk_bf16_f32 v51, v56, v57
	v_mul_f32_e32 v56, 0xbfb8aa3b, v58
	v_mul_f32_e32 v57, 0xbfb8aa3b, v59
	v_exp_f32_e32 v56, v56
	v_exp_f32_e32 v57, v57
	v_add_f32_e32 v56, 1.0, v56
	v_add_f32_e32 v57, 1.0, v57
	v_rcp_f32_e32 v56, v56
	v_rcp_f32_e32 v57, v57
	s_nop 0
	v_pk_mul_f32 v[56:57], v[58:59], v[56:57]
	s_nop 0
	v_pk_mul_f32 v[52:53], v[52:53], v[56:57]
	s_nop 0
	v_cvt_pk_bf16_f32 v52, v52, v53
	v_mul_f32_e32 v53, 0xbfb8aa3b, v60
	v_exp_f32_e32 v53, v53
	s_nop 0
	v_add_f32_e32 v53, 1.0, v53
	v_rcp_f32_e32 v56, v53
	v_mul_f32_e32 v53, 0xbfb8aa3b, v61
	v_exp_f32_e32 v53, v53
	s_nop 0
	v_add_f32_e32 v53, 1.0, v53
	v_rcp_f32_e32 v57, v53
	s_nop 0
	v_pk_mul_f32 v[56:57], v[60:61], v[56:57]
	s_nop 0
	v_pk_mul_f32 v[54:55], v[54:55], v[56:57]
	s_nop 0
	v_cvt_pk_bf16_f32 v53, v54, v55
	global_store_dwordx4 v[72:73], v[50:53], off nt
	v_mov_b32_e32 v58, v174
	v_pk_mul_f32 v[46:47], v[46:47], v[58:59] op_sel_hi:[1,0]
	v_pk_mul_f32 v[54:55], v[38:39], v[58:59] op_sel_hi:[1,0]
	v_pk_mul_f32 v[38:39], v[36:37], v[58:59] op_sel_hi:[1,0]
	v_pk_mul_f32 v[36:37], v[34:35], v[58:59] op_sel_hi:[1,0]
	v_mul_f32_e32 v34, 0xbfb8aa3b, v46
	v_mul_f32_e32 v35, 0xbfb8aa3b, v47
	v_exp_f32_e32 v34, v34
	v_exp_f32_e32 v35, v35
	v_pk_mul_f32 v[48:49], v[48:49], v[58:59] op_sel_hi:[1,0]
	v_pk_mul_f32 v[40:41], v[40:41], v[58:59] op_sel_hi:[1,0]
	v_add_f32_e32 v34, 1.0, v34
	v_add_f32_e32 v35, 1.0, v35
	v_rcp_f32_e32 v34, v34
	v_rcp_f32_e32 v35, v35
	v_pk_mul_f32 v[42:43], v[42:43], v[58:59] op_sel_hi:[1,0]
	v_pk_mul_f32 v[44:45], v[44:45], v[58:59] op_sel_hi:[1,0]
	v_add_u32_e32 v56, 0x90, v140
	v_pk_mul_f32 v[34:35], v[46:47], v[34:35]
	v_mad_i64_i32 v[56:57], s[22:23], v56, s73, v[142:143]
	v_pk_mul_f32 v[34:35], v[54:55], v[34:35]
	v_lshl_add_u64 v[56:57], v[56:57], 0, v[144:145]
	v_cvt_pk_bf16_f32 v34, v34, v35
	v_mul_f32_e32 v35, 0xbfb8aa3b, v48
	v_exp_f32_e32 v35, v35
	s_nop 0
	v_add_f32_e32 v35, 1.0, v35
	v_rcp_f32_e32 v46, v35
	v_mul_f32_e32 v35, 0xbfb8aa3b, v49
	v_exp_f32_e32 v35, v35
	s_nop 0
	v_add_f32_e32 v35, 1.0, v35
	v_rcp_f32_e32 v47, v35
	s_nop 0
	v_pk_mul_f32 v[46:47], v[48:49], v[46:47]
	s_nop 0
	v_pk_mul_f32 v[40:41], v[40:41], v[46:47]
	s_nop 0
	v_cvt_pk_bf16_f32 v35, v40, v41
	v_mul_f32_e32 v40, 0xbfb8aa3b, v42
	v_mul_f32_e32 v41, 0xbfb8aa3b, v43
	v_exp_f32_e32 v40, v40
	v_exp_f32_e32 v41, v41
	v_add_f32_e32 v40, 1.0, v40
	v_add_f32_e32 v41, 1.0, v41
	v_rcp_f32_e32 v40, v40
	v_rcp_f32_e32 v41, v41
	s_nop 0
	v_pk_mul_f32 v[40:41], v[42:43], v[40:41]
	s_nop 0
	v_pk_mul_f32 v[36:37], v[36:37], v[40:41]
	s_nop 0
	v_cvt_pk_bf16_f32 v36, v36, v37
	v_mul_f32_e32 v37, 0xbfb8aa3b, v44
	v_exp_f32_e32 v37, v37
	s_nop 0
	v_add_f32_e32 v37, 1.0, v37
	v_rcp_f32_e32 v40, v37
	v_mul_f32_e32 v37, 0xbfb8aa3b, v45
	v_exp_f32_e32 v37, v37
	s_nop 0
	v_add_f32_e32 v37, 1.0, v37
	v_rcp_f32_e32 v41, v37
	s_nop 0
	v_pk_mul_f32 v[40:41], v[44:45], v[40:41]
	s_nop 0
	v_pk_mul_f32 v[38:39], v[38:39], v[40:41]
	s_nop 0
	v_cvt_pk_bf16_f32 v37, v38, v39
	global_store_dwordx4 v[56:57], v[34:37], off nt
	v_mov_b32_e32 v42, v176
	v_pk_mul_f32 v[30:31], v[30:31], v[42:43] op_sel_hi:[1,0]
	v_pk_mul_f32 v[38:39], v[22:23], v[42:43] op_sel_hi:[1,0]
	v_pk_mul_f32 v[22:23], v[20:21], v[42:43] op_sel_hi:[1,0]
	v_pk_mul_f32 v[20:21], v[18:19], v[42:43] op_sel_hi:[1,0]
	v_mul_f32_e32 v18, 0xbfb8aa3b, v30
	v_mul_f32_e32 v19, 0xbfb8aa3b, v31
	v_exp_f32_e32 v18, v18
	v_exp_f32_e32 v19, v19
	v_pk_mul_f32 v[32:33], v[32:33], v[42:43] op_sel_hi:[1,0]
	v_pk_mul_f32 v[24:25], v[24:25], v[42:43] op_sel_hi:[1,0]
	v_add_f32_e32 v18, 1.0, v18
	v_add_f32_e32 v19, 1.0, v19
; __device__ __forceinline__ unsigned cvt_pk_bf16(float lo, float hi) { f32x2c_t v = {lo, hi}; bf16x2c_t b = __builtin_convertvector(v, bf16x2c_t); return __builtin_bit_cast(unsigned, b); }
;     __device__ __forceinline__ static float sw(float g, float u) { return g * __builtin_amdgcn_rcpf(1.f + __builtin_amdgcn_exp2f(-1.4426950408889634f * g)) * u; }
;     __device__ __forceinline__ void operator()(const f32x4 (&acc)[2][2][4][2], const Unit& u, int wr, int wc, int fr, int fq) const {
;         const int row0 = u.pm * BM + wr * 64 + fr, col0 = u.pn * HALF + wc * 32 + 8 * fq;
; #pragma unroll
;         for (int ai = 0; ai < 2; ++ai)
; #pragma unroll
;             for (int m = 0; m < 4; ++m) { bf16_t* rowp = O + (size_t)(row0 + ai * HALF + m * 16) * ldc + col0;
;                 const float r_ = rs[row0 + ai * HALF + m * 16];
;                 const f32x4 g0 = acc[ai][0][m][0] * r_, g1 = acc[ai][0][m][1] * r_, u0 = acc[ai][1][m][0] * r_, u1 = acc[ai][1][m][1] * r_;
;                 u32x4 w; w.x = cvt_pk_bf16(sw(g0[0], u0[0]), sw(g0[1], u0[1])); w.y = cvt_pk_bf16(sw(g0[2], u0[2]), sw(g0[3], u0[3]));
;                 w.z = cvt_pk_bf16(sw(g1[0], u1[0]), sw(g1[1], u1[1])); w.w = cvt_pk_bf16(sw(g1[2], u1[2]), sw(g1[3], u1[3]));
;                 *(u32x4*)rowp = w; }
	v_rcp_f32_e32 v18, v18
	v_rcp_f32_e32 v19, v19
	v_pk_mul_f32 v[26:27], v[26:27], v[42:43] op_sel_hi:[1,0]
	v_pk_mul_f32 v[28:29], v[28:29], v[42:43] op_sel_hi:[1,0]
	v_add_u32_e32 v40, 0xa0, v140
	v_pk_mul_f32 v[18:19], v[30:31], v[18:19]
	v_mad_i64_i32 v[40:41], s[22:23], v40, s73, v[142:143]
	v_pk_mul_f32 v[18:19], v[38:39], v[18:19]
	v_lshl_add_u64 v[40:41], v[40:41], 0, v[144:145]
	v_cvt_pk_bf16_f32 v18, v18, v19
	v_mul_f32_e32 v19, 0xbfb8aa3b, v32
	v_exp_f32_e32 v19, v19
	s_nop 0
	v_add_f32_e32 v19, 1.0, v19
	v_rcp_f32_e32 v30, v19
	v_mul_f32_e32 v19, 0xbfb8aa3b, v33
	v_exp_f32_e32 v19, v19
	s_nop 0
	v_add_f32_e32 v19, 1.0, v19
	v_rcp_f32_e32 v31, v19
	s_nop 0
	v_pk_mul_f32 v[30:31], v[32:33], v[30:31]
	s_nop 0
	v_pk_mul_f32 v[24:25], v[24:25], v[30:31]
	s_nop 0
	v_cvt_pk_bf16_f32 v19, v24, v25
	v_mul_f32_e32 v24, 0xbfb8aa3b, v26
	v_mul_f32_e32 v25, 0xbfb8aa3b, v27
	v_exp_f32_e32 v24, v24
	v_exp_f32_e32 v25, v25
	v_add_f32_e32 v24, 1.0, v24
	v_add_f32_e32 v25, 1.0, v25
	v_rcp_f32_e32 v24, v24
	v_rcp_f32_e32 v25, v25
	s_nop 0
	v_pk_mul_f32 v[24:25], v[26:27], v[24:25]
	s_nop 0
	v_pk_mul_f32 v[20:21], v[20:21], v[24:25]
	s_nop 0
	v_cvt_pk_bf16_f32 v20, v20, v21
	v_mul_f32_e32 v21, 0xbfb8aa3b, v28
	v_exp_f32_e32 v21, v21
	s_nop 0
	v_add_f32_e32 v21, 1.0, v21
	v_rcp_f32_e32 v24, v21
	v_mul_f32_e32 v21, 0xbfb8aa3b, v29
	v_exp_f32_e32 v21, v21
	s_nop 0
	v_add_f32_e32 v21, 1.0, v21
	v_rcp_f32_e32 v25, v21
	s_nop 0
	v_pk_mul_f32 v[24:25], v[28:29], v[24:25]
	s_nop 0
	v_pk_mul_f32 v[22:23], v[22:23], v[24:25]
	s_nop 0
	v_cvt_pk_bf16_f32 v21, v22, v23
	global_store_dwordx4 v[40:41], v[18:21], off nt
	v_mov_b32_e32 v26, v178
	v_pk_mul_f32 v[14:15], v[14:15], v[26:27] op_sel_hi:[1,0]
	v_pk_mul_f32 v[22:23], v[4:5], v[26:27] op_sel_hi:[1,0]
	v_pk_mul_f32 v[4:5], v[2:3], v[26:27] op_sel_hi:[1,0]
	v_mul_f32_e32 v2, 0xbfb8aa3b, v14
	v_mul_f32_e32 v3, 0xbfb8aa3b, v15
	v_exp_f32_e32 v2, v2
	v_exp_f32_e32 v3, v3
	v_pk_mul_f32 v[6:7], v[6:7], v[26:27] op_sel_hi:[1,0]
	v_pk_mul_f32 v[16:17], v[16:17], v[26:27] op_sel_hi:[1,0]
	v_add_f32_e32 v2, 1.0, v2
	v_add_f32_e32 v3, 1.0, v3
	v_rcp_f32_e32 v2, v2
	v_rcp_f32_e32 v3, v3
	v_pk_mul_f32 v[8:9], v[8:9], v[26:27] op_sel_hi:[1,0]
	v_pk_mul_f32 v[10:11], v[10:11], v[26:27] op_sel_hi:[1,0]
	v_pk_mul_f32 v[12:13], v[12:13], v[26:27] op_sel_hi:[1,0]
	v_pk_mul_f32 v[2:3], v[14:15], v[2:3]
	v_add_u32_e32 v24, 0xb0, v140
	v_pk_mul_f32 v[2:3], v[6:7], v[2:3]
	v_mad_i64_i32 v[24:25], s[22:23], v24, s73, v[142:143]
	v_cvt_pk_bf16_f32 v2, v2, v3
	v_mul_f32_e32 v3, 0xbfb8aa3b, v16
	v_exp_f32_e32 v3, v3
	v_lshl_add_u64 v[24:25], v[24:25], 0, v[144:145]
	v_add_f32_e32 v3, 1.0, v3
	v_rcp_f32_e32 v6, v3
	v_mul_f32_e32 v3, 0xbfb8aa3b, v17
	v_exp_f32_e32 v3, v3
	s_nop 0
	v_add_f32_e32 v3, 1.0, v3
	v_rcp_f32_e32 v7, v3
	s_nop 0
	v_pk_mul_f32 v[6:7], v[16:17], v[6:7]
	s_nop 0
	v_pk_mul_f32 v[6:7], v[8:9], v[6:7]
	s_nop 0
	v_cvt_pk_bf16_f32 v3, v6, v7
	v_mul_f32_e32 v6, 0xbfb8aa3b, v10
	v_mul_f32_e32 v7, 0xbfb8aa3b, v11
	v_exp_f32_e32 v6, v6
	v_exp_f32_e32 v7, v7
	v_add_f32_e32 v6, 1.0, v6
	v_add_f32_e32 v7, 1.0, v7
	v_rcp_f32_e32 v6, v6
	v_rcp_f32_e32 v7, v7
	s_nop 0
	v_pk_mul_f32 v[6:7], v[10:11], v[6:7]
	s_nop 0
	v_pk_mul_f32 v[4:5], v[4:5], v[6:7]
	s_nop 0
	v_cvt_pk_bf16_f32 v4, v4, v5
	v_mul_f32_e32 v5, 0xbfb8aa3b, v12
	v_exp_f32_e32 v5, v5
	s_nop 0
	v_add_f32_e32 v5, 1.0, v5
	v_rcp_f32_e32 v6, v5
	v_mul_f32_e32 v5, 0xbfb8aa3b, v13
	v_exp_f32_e32 v5, v5
	s_nop 0
	v_add_f32_e32 v5, 1.0, v5
	v_rcp_f32_e32 v7, v5
	s_nop 0
	v_pk_mul_f32 v[6:7], v[12:13], v[6:7]
	s_nop 0
	v_pk_mul_f32 v[6:7], v[22:23], v[6:7]
	s_nop 0
	v_cvt_pk_bf16_f32 v5, v6, v7
	global_store_dwordx4 v[24:25], v[2:5], off nt
	s_cbranch_vccnz .LBB0_700
	s_andn2_b64 vcc, exec, s[26:27]
	s_cbranch_vccnz .LBB0_699
	s_barrier
	s_branch .LBB0_699
